# band K/V tile loads as global_load (not flat): the step barrier's lgkmcnt(0) no longer waits for them; plus dead canonicalisation removed and odd-tile DMA test moved ahead of the K reads
# speedup vs baseline: 1.0265x; 1.0049x over previous
; DI void band_item(const Params& P, char* lds_blk, int layer, int bp) {
;     ...
;     auto gload = [&](int kt) {
; #pragma unroll
;         for (int j = 0; j < 2; ++j) {
;             const ptrdiff_t ro = ((ptrdiff_t)(64 * kt + srow + 32 * j) - 128) * (ptrdiff_t)rs + sch * 8;
;             rk[j] = *(const u32x4*)(kp + ro); rv[j] = *(const u32x4*)(vp + ro);
;         }
;     };
;     ...
;         if (kt + 1 < 4) gload(kt + 1);
.LBB0_214:
	s_cmp_lg_u32 s65, 2
	s_cselect_b64 s[22:23], -1, 0
	s_cmp_eq_u32 s65, 2
	s_cbranch_scc1 .LBB0_216
	v_lshl_add_u64 v[34:35], v[120:121], 0, v[0:1]
	s_waitcnt vmcnt(0)
	global_load_dwordx4 v[82:85], v[34:35], off
	v_lshl_add_u64 v[34:35], v[118:119], 0, v[0:1]
	global_load_dwordx4 v[86:89], v[34:35], off
	v_lshl_add_u64 v[34:35], v[116:117], 0, v[0:1]
	global_load_dwordx4 v[90:93], v[34:35], off
	v_lshl_add_u64 v[34:35], v[114:115], 0, v[0:1]
	global_load_dwordx4 v[94:97], v[34:35], off
	s_cmp_eq_u32 s65, 1
	s_cbranch_scc0 .Lb3_no0
	s_cmp_eq_u32 s100, 1
	s_cbranch_scc0 .Lb3_no0
	s_mul_i32 s0, s16, 3
	v_lshl_add_u64 v[34:35], v[120:121], 0, v[0:1]
	v_subrev_co_u32_e32 v254, vcc, s0, v34
	s_nop 1
	v_subbrev_co_u32_e32 v255, vcc, 0, v35, vcc
	global_load_dwordx4 v[238:241], v[254:255], off
	v_lshl_add_u64 v[34:35], v[118:119], 0, v[0:1]
	v_subrev_co_u32_e32 v254, vcc, s0, v34
	s_nop 1
	v_subbrev_co_u32_e32 v255, vcc, 0, v35, vcc
	global_load_dwordx4 v[242:245], v[254:255], off
	v_lshl_add_u64 v[34:35], v[116:117], 0, v[0:1]
	v_subrev_co_u32_e32 v254, vcc, s0, v34
	s_nop 1
	v_subbrev_co_u32_e32 v255, vcc, 0, v35, vcc
	global_load_dwordx4 v[246:249], v[254:255], off
	v_lshl_add_u64 v[34:35], v[114:115], 0, v[0:1]
	v_subrev_co_u32_e32 v254, vcc, s0, v34
	s_nop 1
	v_subbrev_co_u32_e32 v255, vcc, 0, v35, vcc
	global_load_dwordx4 v[250:253], v[254:255], off

; #define LAS __attribute__((address_space(3)))
; #define MFMA(a, b, c) __builtin_amdgcn_mfma_f32_32x32x16_bf16((a), (b), (c), 0, 0, 0)
; template <typename F>
; DI void diff_step(lptr sK, lptr sV, int kx0, int vl0, const bf16x8 (&qf)[4], float& m, float& l, f32x16 (&O)[4],
;                   const LAS float* tb, bool far, float cfar, int lane, F&& mid) {
;     ...
;     lptr kr = sK + r * 256;
;     bf16x8 kf[8];
; #pragma unroll
;     for (int s = 0; s < 4; ++s) {
;         const int co = (kx0 ^ (2 * s)) * 16;
;         kf[2 * s] = *(const LAS bf16x8*)(kr + co);
;         kf[2 * s + 1] = *(const LAS bf16x8*)(kr + 8192 + co);
;     }
;     __builtin_amdgcn_sched_barrier(0);
;     mid();
;     __builtin_amdgcn_sched_barrier(0);
; #pragma unroll
;     for (int s = 0; s < 4; ++s) { p0 = MFMA(kf[2 * s], qf[s], p0); p1 = MFMA(kf[2 * s + 1], qf[s], p1); }
.Ldu_A:
	s_waitcnt vmcnt(0)
	s_waitcnt lgkmcnt(0)
	s_barrier
	ds_read_b128 v[80:83], v14
	ds_read_b128 v[84:87], v14 offset:8192
	ds_read_b128 v[120:123], v15
	ds_read_b128 v[6:9], v15 offset:8192
	ds_read_b128 v[116:119], v221
	ds_read_b128 v[2:5], v221 offset:8192
	ds_read_b128 v[10:13], v222
	ds_read_b128 v[112:115], v222 offset:8192
	v_add_u32_e32 v220, 1, v220
	s_add_u32 s72, s63, 0x8000
	s_mov_b32 m0, s72
	s_nop 0
	global_load_lds_dwordx4 v170, s[64:65]
	s_add_u32 s72, s63, 0xc000
	s_mov_b32 m0, s72
	s_nop 0
	global_load_lds_dwordx4 v170, s[70:71]
	s_add_u32 s72, s63, 0x8400
	s_mov_b32 m0, s72
	s_nop 0
	global_load_lds_dwordx4 v172, s[64:65]
	s_add_u32 s72, s63, 0xc400
	s_mov_b32 m0, s72
	s_nop 0
	global_load_lds_dwordx4 v172, s[70:71]
	s_add_u32 s64, s64, 0xe0000
	s_addc_u32 s65, s65, 0
	s_add_u32 s70, s70, 0xe0000
	s_addc_u32 s71, s71, 0
	v_cmp_gt_i32_e32 vcc, s42, v217
	s_waitcnt lgkmcnt(7)
	v_mfma_f32_32x32x16_bf16 v[96:111], v[80:83], v[144:147], 0
	s_waitcnt lgkmcnt(6)
	v_mfma_f32_32x32x16_bf16 v[80:95], v[84:87], v[144:147], 0
	s_waitcnt lgkmcnt(5)
	v_mfma_f32_32x32x16_bf16 v[96:111], v[120:123], v[148:151], v[96:111]
	s_waitcnt lgkmcnt(4)
	v_mfma_f32_32x32x16_bf16 v[80:95], v[6:9], v[148:151], v[80:95]
	s_waitcnt lgkmcnt(3)
	v_mfma_f32_32x32x16_bf16 v[96:111], v[116:119], v[152:155], v[96:111]
	s_waitcnt lgkmcnt(2)
	v_mfma_f32_32x32x16_bf16 v[80:95], v[2:5], v[152:155], v[80:95]
	ds_read_b64_tr_b16 v[2:3], v199 offset:16384
	ds_read_b64_tr_b16 v[4:5], v210 offset:18432
	ds_read_b64_tr_b16 v[6:7], v211 offset:16384
	ds_read_b64_tr_b16 v[8:9], v212 offset:18432
	s_waitcnt lgkmcnt(5)
	v_mfma_f32_32x32x16_bf16 v[96:111], v[10:13], v[156:159], v[96:111]
	ds_read_b64_tr_b16 v[10:11], v213 offset:16384
	ds_read_b64_tr_b16 v[12:13], v214 offset:18432
	ds_read_b64_tr_b16 v[160:161], v215 offset:16384
	ds_read_b64_tr_b16 v[162:163], v216 offset:18432
	s_waitcnt lgkmcnt(8)
	v_mfma_f32_32x32x16_bf16 v[80:95], v[112:115], v[156:159], v[80:95]
	s_and_saveexec_b64 s[22:23], vcc
	s_xor_b64 s[22:23], exec, s[22:23]
	s_cbranch_execz .LBB0_258_a
	ds_read2_b32 v[112:113], v218 offset0:58 offset1:59
	ds_read2_b32 v[114:115], v218 offset0:56 offset1:57
	ds_read2_b32 v[116:117], v218 offset0:50 offset1:51
	ds_read2_b32 v[118:119], v218 offset0:48 offset1:49
	ds_read2_b32 v[120:121], v218 offset0:26 offset1:27
	ds_read2_b32 v[122:123], v218 offset0:24 offset1:25
	ds_read2_b32 v[124:125], v218 offset0:18 offset1:19
	ds_read2_b32 v[126:127], v218 offset0:16 offset1:17
	ds_read2_b32 v[128:129], v218 offset0:42 offset1:43
	ds_read2_b32 v[130:131], v218 offset0:40 offset1:41
	ds_read2_b32 v[132:133], v218 offset0:34 offset1:35
	ds_read2_b32 v[134:135], v218 offset0:32 offset1:33
	ds_read2_b32 v[136:137], v218 offset0:10 offset1:11
	ds_read2_b32 v[138:139], v218 offset0:8 offset1:9
	ds_read2_b32 v[140:141], v218 offset0:2 offset1:3
	ds_read2_b32 v[142:143], v218 offset1:1
	s_nop 7
	s_nop 7
	s_nop 3
	s_waitcnt lgkmcnt(14)
	v_fma_f32 v96, v96, v178, v113
	s_waitcnt lgkmcnt(11)
	v_fma_f32 v80, v80, v178, v121
	v_fma_f32 v97, v97, v178, v112
	v_fma_f32 v81, v81, v178, v120
	v_fma_f32 v98, v98, v178, v115
	s_waitcnt lgkmcnt(10)
	v_fma_f32 v82, v82, v178, v123
	v_fma_f32 v99, v99, v178, v114
	v_fma_f32 v83, v83, v178, v122
	v_max3_f32 v112, v96, v97, v80
	v_fma_f32 v100, v100, v178, v117
	v_fma_f32 v101, v101, v178, v116
	v_fma_f32 v102, v102, v178, v119
	s_nop 0
	v_max3_f32 v113, v98, v99, v81
	v_fma_f32 v103, v103, v178, v118
	v_max3_f32 v112, v112, v82, v83
	s_waitcnt lgkmcnt(9)
	v_fma_f32 v84, v84, v178, v125
	v_fma_f32 v85, v85, v178, v124
	s_waitcnt lgkmcnt(8)
	v_fma_f32 v86, v86, v178, v127
	v_fma_f32 v87, v87, v178, v126
	v_max3_f32 v113, v113, v102, v103
	v_max3_f32 v112, v112, v100, v101
	s_waitcnt lgkmcnt(7)
	v_fma_f32 v104, v104, v178, v129
	v_fma_f32 v105, v105, v178, v128
	s_waitcnt lgkmcnt(6)
	v_fma_f32 v106, v106, v178, v131
	v_fma_f32 v107, v107, v178, v130
	v_max3_f32 v113, v113, v86, v87
	v_max3_f32 v112, v112, v84, v85
	s_waitcnt lgkmcnt(3)
	v_fma_f32 v88, v88, v178, v137
	v_fma_f32 v89, v89, v178, v136
	s_waitcnt lgkmcnt(2)
	v_fma_f32 v90, v90, v178, v139
	v_fma_f32 v91, v91, v178, v138
	v_max3_f32 v113, v113, v106, v107
	v_max3_f32 v112, v112, v104, v105
	v_fma_f32 v108, v108, v178, v133
	v_fma_f32 v109, v109, v178, v132
	v_fma_f32 v110, v110, v178, v135
	v_fma_f32 v111, v111, v178, v134
	s_nop 0
	v_max3_f32 v113, v113, v90, v91
	v_max3_f32 v112, v112, v88, v89
	s_waitcnt lgkmcnt(1)
	v_fma_f32 v92, v92, v178, v141
	v_fma_f32 v93, v93, v178, v140
	s_waitcnt lgkmcnt(0)
	v_fma_f32 v94, v94, v178, v143
	v_fma_f32 v95, v95, v178, v142
	v_max3_f32 v113, v113, v110, v111
	v_max3_f32 v112, v112, v108, v109
	s_nop 0
	v_max3_f32 v112, v112, v92, v93
	v_max3_f32 v113, v113, v94, v95
	s_nop 0
	v_max_f32_e32 v113, v113, v113
	v_max_f32_e32 v112, v112, v112
	v_max_f32_e32 v112, v112, v113
	v_mov_b32_e32 v113, v112
	s_nop 1
	v_permlane32_swap_b32_e32 v112, v113
	v_max_f32_e32 v113, v113, v113
	v_max_f32_e32 v112, v112, v112
	v_max_f32_e32 v112, v112, v113
	v_sub_f32_e32 v113, v112, v226
	v_cmp_lt_f32_e32 vcc, s45, v113
	v_max_f32_e32 v112, v226, v112
	s_nop 0
	v_cndmask_b32_e32 v227, v226, v112, vcc
	v_sub_f32 v112, v96, v227
	v_sub_f32 v128, v80, v227
	v_sub_f32 v113, v97, v227
	v_sub_f32 v129, v81, v227
	v_sub_f32 v114, v98, v227
	v_sub_f32 v130, v82, v227
	v_sub_f32 v115, v99, v227
	v_sub_f32 v131, v83, v227
	v_sub_f32 v116, v100, v227
	v_sub_f32 v132, v84, v227
	v_sub_f32 v117, v101, v227
	v_sub_f32 v133, v85, v227
	v_sub_f32 v118, v102, v227
	v_sub_f32 v134, v86, v227
	v_sub_f32 v119, v103, v227
	v_sub_f32 v135, v87, v227
	v_sub_f32 v120, v104, v227
	v_sub_f32 v136, v88, v227
	v_sub_f32 v121, v105, v227
	v_sub_f32 v137, v89, v227
	v_sub_f32 v122, v106, v227
	v_sub_f32 v138, v90, v227
	v_sub_f32 v123, v107, v227
	v_sub_f32 v139, v91, v227
	v_sub_f32 v124, v108, v227
	v_sub_f32 v140, v92, v227
	v_sub_f32 v125, v109, v227
	v_sub_f32 v141, v93, v227
	v_sub_f32 v126, v110, v227
	v_sub_f32 v142, v94, v227
	v_sub_f32 v127, v111, v227
	v_sub_f32 v143, v95, v227

; #define LAS __attribute__((address_space(3)))
; DI void diff_item(const Params& P, char* lds, int layer, int pair, int qt, int& tab_head) {
;     ...
;     auto issue = [&](int kt, int buf) {
;         const size_t to = (size_t)(64 * kt) * PO;
; #pragma unroll
;         for (int i = 0; i < 2; ++i) {
;             glds16(kg + to + goff[i], (unsigned)__builtin_amdgcn_readfirstlane(lds0 + buf * 32768 + (2 * w + i) * 1024));
;             glds16(vg + to + goff[i], (unsigned)__builtin_amdgcn_readfirstlane(lds0 + buf * 32768 + 16384 + (2 * w + i) * 1024));
;         }
;     };
;     issue(0, 0);
;     bf16x8 qf[4];
; #pragma unroll
;     for (int s = 0; s < 4; ++s) qf[s] = *(const bf16x8*)(base + (size_t)qpos * PO + OFF_CQ + head * 128 + mp * 64 + 16 * s + 8 * hh);
;     float m = -1e30f, l = 0.f;
;     f32x16 O[4];
; #pragma unroll
;     for (int dt = 0; dt < 4; ++dt)
; #pragma unroll
;         for (int i = 0; i < 16; ++i) O[dt][i] = 0.f;
;     const int sig_r = ((r & 3) << 2) | ((r >> 2) & 3);
;     const int kx0 = (8 * mp + hh) ^ sig_r;
;     const int i16 = lane & 15, q = i16 >> 2, pp = i16 & 3, blk = (lane >> 4) & 1;
;     const int vl0 = (4 * hh + q) * 256 + (16 * ((q << 2) | (blk << 1) | ((pp >> 1) ^ hh)) + 8 * (pp & 1));
;     const int nkt = 2 * qt + 2;
;     for (int kt = 0; kt < nkt; ++kt) {
;         asm volatile("s_waitcnt vmcnt(0)" ::: "memory");
;         __syncthreads();
;         auto mid = [&]() { if (kt + 1 < nkt) issue(kt + 1, (kt + 1) & 1); };
;         if (64 * kt <= q0 + 32 * qs + 31) {
;             const bool far = (q0 + 32 * qs) - (64 * kt + 63) >= 1536;
;             const LAS float* tb = (const LAS float*)ctab + (qpos - 64 * kt - 4 * hh + 64 - 63);
;             lptr bufp = (lptr)lds + (kt & 1) * 32768;
;             diff_step(bufp, bufp + 16384, kx0, vl0, qf, m, l, O, tb, far, cfar, lane, mid);
.Ldu_B:
	s_waitcnt vmcnt(0)
	s_sub_i32 s22, s50, 64
	v_cmp_le_u32_e32 vcc, s22, v200
	v_add_u32_e32 v0, 1, v220
	s_waitcnt lgkmcnt(0)
	s_barrier
	s_and_saveexec_b64 s[22:23], vcc
	s_xor_b64 s[40:41], exec, s[22:23]
	s_cbranch_execz .LBB0_263_b
	v_add_u32_e32 v220, 1, v220
	v_cmp_gt_u32_e32 vcc, s49, v220
	ds_read_b128 v[80:83], v14 offset:32768
	ds_read_b128 v[84:87], v14 offset:40960
	ds_read_b128 v[120:123], v15 offset:32768
	ds_read_b128 v[6:9], v15 offset:40960
	ds_read_b128 v[116:119], v221 offset:32768
	ds_read_b128 v[2:5], v221 offset:40960
	ds_read_b128 v[10:13], v222 offset:32768
	ds_read_b128 v[112:115], v222 offset:40960
	s_and_saveexec_b64 s[22:23], vcc
	s_cbranch_execz .LBB0_256_b
	s_mov_b32 s72, s63
	s_mov_b32 m0, s72
	s_nop 0
	global_load_lds_dwordx4 v170, s[64:65]
	s_add_u32 s72, s63, 0x4000
	s_mov_b32 m0, s72
	s_nop 0
	global_load_lds_dwordx4 v170, s[70:71]
	s_add_u32 s72, s63, 0x400
	s_mov_b32 m0, s72
	s_nop 0
	global_load_lds_dwordx4 v172, s[64:65]
	s_add_u32 s72, s63, 0x4400
	s_mov_b32 m0, s72
	s_nop 0
	global_load_lds_dwordx4 v172, s[70:71]
	s_add_u32 s64, s64, 0xe0000
	s_addc_u32 s65, s65, 0
	s_add_u32 s70, s70, 0xe0000
	s_addc_u32 s71, s71, 0
.LBB0_256_b:
	s_or_b64 exec, exec, s[22:23]
	v_cmp_gt_i32_e32 vcc, s42, v217
	s_waitcnt lgkmcnt(7)
	v_mfma_f32_32x32x16_bf16 v[96:111], v[80:83], v[144:147], 0
	s_waitcnt lgkmcnt(6)
	v_mfma_f32_32x32x16_bf16 v[80:95], v[84:87], v[144:147], 0
	s_waitcnt lgkmcnt(5)
	v_mfma_f32_32x32x16_bf16 v[96:111], v[120:123], v[148:151], v[96:111]
	s_waitcnt lgkmcnt(4)
	v_mfma_f32_32x32x16_bf16 v[80:95], v[6:9], v[148:151], v[80:95]
	s_waitcnt lgkmcnt(3)
	v_mfma_f32_32x32x16_bf16 v[96:111], v[116:119], v[152:155], v[96:111]
	s_waitcnt lgkmcnt(2)
	v_mfma_f32_32x32x16_bf16 v[80:95], v[2:5], v[152:155], v[80:95]
	ds_read_b64_tr_b16 v[2:3], v199 offset:49152
	ds_read_b64_tr_b16 v[4:5], v210 offset:51200
	ds_read_b64_tr_b16 v[6:7], v211 offset:49152
	ds_read_b64_tr_b16 v[8:9], v212 offset:51200
	s_waitcnt lgkmcnt(5)
	v_mfma_f32_32x32x16_bf16 v[96:111], v[10:13], v[156:159], v[96:111]
	ds_read_b64_tr_b16 v[10:11], v213 offset:49152
	ds_read_b64_tr_b16 v[12:13], v214 offset:51200
	ds_read_b64_tr_b16 v[160:161], v215 offset:49152
	ds_read_b64_tr_b16 v[162:163], v216 offset:51200
	s_waitcnt lgkmcnt(8)
	v_mfma_f32_32x32x16_bf16 v[80:95], v[112:115], v[156:159], v[80:95]
	s_and_saveexec_b64 s[22:23], vcc
	s_xor_b64 s[22:23], exec, s[22:23]
	s_cbranch_execz .LBB0_258_b
	ds_read2_b32 v[112:113], v218 offset0:58 offset1:59
	ds_read2_b32 v[114:115], v218 offset0:56 offset1:57
	ds_read2_b32 v[116:117], v218 offset0:50 offset1:51
	ds_read2_b32 v[118:119], v218 offset0:48 offset1:49
	ds_read2_b32 v[120:121], v218 offset0:26 offset1:27
	ds_read2_b32 v[122:123], v218 offset0:24 offset1:25
	ds_read2_b32 v[124:125], v218 offset0:18 offset1:19
	ds_read2_b32 v[126:127], v218 offset0:16 offset1:17
	ds_read2_b32 v[128:129], v218 offset0:42 offset1:43
	ds_read2_b32 v[130:131], v218 offset0:40 offset1:41
	ds_read2_b32 v[132:133], v218 offset0:34 offset1:35
	ds_read2_b32 v[134:135], v218 offset0:32 offset1:33
	ds_read2_b32 v[136:137], v218 offset0:10 offset1:11
	ds_read2_b32 v[138:139], v218 offset0:8 offset1:9
	ds_read2_b32 v[140:141], v218 offset0:2 offset1:3
	ds_read2_b32 v[142:143], v218 offset1:1
	s_nop 7
	s_nop 7
	s_nop 3
	s_waitcnt lgkmcnt(14)
	v_fma_f32 v96, v96, v178, v113
	s_waitcnt lgkmcnt(11)
	v_fma_f32 v80, v80, v178, v121
	v_fma_f32 v97, v97, v178, v112
	v_fma_f32 v81, v81, v178, v120
	v_fma_f32 v98, v98, v178, v115
	s_waitcnt lgkmcnt(10)
	v_fma_f32 v82, v82, v178, v123
	v_fma_f32 v99, v99, v178, v114
	v_fma_f32 v83, v83, v178, v122
	v_max3_f32 v112, v96, v97, v80
	v_fma_f32 v100, v100, v178, v117
	v_fma_f32 v101, v101, v178, v116
	v_fma_f32 v102, v102, v178, v119
	s_nop 0
	v_max3_f32 v113, v98, v99, v81
	v_fma_f32 v103, v103, v178, v118
	v_max3_f32 v112, v112, v82, v83
	s_waitcnt lgkmcnt(9)
	v_fma_f32 v84, v84, v178, v125
	v_fma_f32 v85, v85, v178, v124
	s_waitcnt lgkmcnt(8)
	v_fma_f32 v86, v86, v178, v127
	v_fma_f32 v87, v87, v178, v126
	v_max3_f32 v113, v113, v102, v103
	v_max3_f32 v112, v112, v100, v101
	s_waitcnt lgkmcnt(7)
	v_fma_f32 v104, v104, v178, v129
	v_fma_f32 v105, v105, v178, v128
	s_waitcnt lgkmcnt(6)
	v_fma_f32 v106, v106, v178, v131
	v_fma_f32 v107, v107, v178, v130
	v_max3_f32 v113, v113, v86, v87
	v_max3_f32 v112, v112, v84, v85
	s_waitcnt lgkmcnt(3)
	v_fma_f32 v88, v88, v178, v137
	v_fma_f32 v89, v89, v178, v136
	s_waitcnt lgkmcnt(2)
	v_fma_f32 v90, v90, v178, v139
	v_fma_f32 v91, v91, v178, v138
	v_max3_f32 v113, v113, v106, v107
	v_max3_f32 v112, v112, v104, v105
	v_fma_f32 v108, v108, v178, v133
	v_fma_f32 v109, v109, v178, v132
	v_fma_f32 v110, v110, v178, v135
	v_fma_f32 v111, v111, v178, v134
	s_nop 0
	v_max3_f32 v113, v113, v90, v91
	v_max3_f32 v112, v112, v88, v89
	s_waitcnt lgkmcnt(1)
	v_fma_f32 v92, v92, v178, v141
	v_fma_f32 v93, v93, v178, v140
	s_waitcnt lgkmcnt(0)
	v_fma_f32 v94, v94, v178, v143
	v_fma_f32 v95, v95, v178, v142
	v_max3_f32 v113, v113, v110, v111
	v_max3_f32 v112, v112, v108, v109
	s_nop 0
	v_max3_f32 v112, v112, v92, v93
	v_max3_f32 v113, v113, v94, v95
	s_nop 0
	v_max_f32_e32 v113, v113, v113
	v_max_f32_e32 v112, v112, v112
	v_max_f32_e32 v112, v112, v113
	v_mov_b32_e32 v113, v112
	s_nop 1
	v_permlane32_swap_b32_e32 v112, v113
	v_max_f32_e32 v113, v113, v113
	v_max_f32_e32 v112, v112, v112
	v_max_f32_e32 v112, v112, v113
	v_sub_f32_e32 v113, v112, v226
	v_cmp_lt_f32_e32 vcc, s45, v113
	v_max_f32_e32 v112, v226, v112
	s_nop 0
	v_cndmask_b32_e32 v227, v226, v112, vcc
	v_sub_f32 v112, v96, v227
	v_sub_f32 v128, v80, v227
	v_sub_f32 v113, v97, v227
	v_sub_f32 v129, v81, v227
	v_sub_f32 v114, v98, v227
	v_sub_f32 v130, v82, v227
	v_sub_f32 v115, v99, v227
	v_sub_f32 v131, v83, v227
	v_sub_f32 v116, v100, v227
	v_sub_f32 v132, v84, v227
	v_sub_f32 v117, v101, v227
	v_sub_f32 v133, v85, v227
	v_sub_f32 v118, v102, v227
	v_sub_f32 v134, v86, v227
	v_sub_f32 v119, v103, v227
	v_sub_f32 v135, v87, v227
	v_sub_f32 v120, v104, v227
	v_sub_f32 v136, v88, v227
	v_sub_f32 v121, v105, v227
	v_sub_f32 v137, v89, v227
	v_sub_f32 v122, v106, v227
	v_sub_f32 v138, v90, v227
	v_sub_f32 v123, v107, v227
	v_sub_f32 v139, v91, v227
	v_sub_f32 v124, v108, v227
	v_sub_f32 v140, v92, v227
	v_sub_f32 v125, v109, v227
	v_sub_f32 v141, v93, v227
	v_sub_f32 v126, v110, v227
	v_sub_f32 v142, v94, v227
	v_sub_f32 v127, v111, v227
	v_sub_f32 v143, v95, v227
